# gate epilogue: packed f32 ops (pk_add/pk_mul/pk_fma) split into two scalar ops each, bit-identical
# speedup vs baseline: 1.0054x; 1.0054x over previous
; DI u32x4* merge_scratch(PREF p, int region) { const int t = tid512(); return (u32x4*)p.fbuf + (size_t)blockIdx.x * 40960 + region * 8192 + (t >> 6) * 1024 + (t & 63); }
; DI void br_store(PREF p, const f32x4 (&acc)[2][2][4][2], int slot) {
;   u32x4* sb = merge_scratch(p, slot);
; #pragma unroll
;   for (int ai = 0; ai < 2; ++ai)
; #pragma unroll
;     for (int bj = 0; bj < 2; ++bj)
; #pragma unroll
;       for (int m = 0; m < 4; ++m) {
;         u32x4 o;
;         o.x = pack2(acc[ai][bj][m][0][0], acc[ai][bj][m][0][1]); o.y = pack2(acc[ai][bj][m][0][2], acc[ai][bj][m][0][3]);
;         o.z = pack2(acc[ai][bj][m][1][0], acc[ai][bj][m][1][1]); o.w = pack2(acc[ai][bj][m][1][2], acc[ai][bj][m][1][3]);
;         sb[((ai * 2 + bj) * 4 + m) * 64] = o;
;       }
; }
; DI void br_flush(PREF p, f32x4 (&acc)[2][2][4][2], int slot) { br_store(p, acc, slot); zero_acc256(acc); }
; DI void gate_reg(PREF p, int l, int n, f32x4 (&acc)[2][2][4][2], int dt) {
;   const u32x4* sbn = merge_scratch(p, n);
;   u32x4* ssum = merge_scratch(p, 4);
;   const int t = tid512(), wid = t >> 6, lane = t & 63, wc = wid & 3, fr = lane & 15;
;   const float* bm = p.b_merge + (size_t)l * 4096 + n * 1024 + dt * 256 + wc * 32 + fr;
;   float bias[2][2];
; #pragma unroll
;   for (int bj = 0; bj < 2; ++bj)
; #pragma unroll
;     for (int nn = 0; nn < 2; ++nn) bias[bj][nn] = bm[bj * 128 + nn * 16];
; #pragma unroll
;   for (int ai = 0; ai < 2; ++ai)
; #pragma unroll
;     for (int bj = 0; bj < 2; ++bj) {
;       __builtin_amdgcn_sched_barrier(0);
;       u32x4 bn[4], pv[4];
; #pragma unroll
;       for (int m = 0; m < 4; ++m) {
;         bn[m] = sbn[((ai * 2 + bj) * 4 + m) * 64];
;         if (n > 0) pv[m] = ssum[((ai * 2 + bj) * 4 + m) * 64];
;       }
; #pragma unroll
;       for (int m = 0; m < 4; ++m) {
;         float b[8]; unpack8(bn[m], b);
;         float v[8];
; #pragma unroll
;         for (int nn = 0; nn < 2; ++nn)
; #pragma unroll
;           for (int j = 0; j < 4; ++j) v[nn * 4 + j] = sigm(acc[ai][bj][m][nn][j] + bias[bj][nn]) * b[nn * 4 + j];
;         if (n > 0) {
;           float o[8]; unpack8(pv[m], o);
; #pragma unroll
;           for (int e = 0; e < 8; ++e) v[e] += o[e];
;         }
;         if (n < 3) ssum[((ai * 2 + bj) * 4 + m) * 64] = pack8(v);
; #pragma unroll
;         for (int nn = 0; nn < 2; ++nn)
; #pragma unroll
.LBB0_108:
	s_or_b64 exec, exec, s[8:9]
	s_lshl_b32 s0, s23, 8
	s_add_u32 s98, s25, s0
	s_addc_u32 s99, s48, 0
	s_lshr_b32 s0, s23, 1
	s_lshl_b32 s0, s0, 12
	s_add_u32 s8, s63, s0
	s_addc_u32 s9, s64, 0
	s_add_u32 s10, s8, 0x20000
	s_addc_u32 s11, s9, 0
	s_add_u32 s42, s8, 0x40000
	s_addc_u32 s43, s9, 0
	s_add_u32 s44, s8, 0x60000
	s_addc_u32 s45, s9, 0
	s_lshl_b32 s0, s23, 1
	v_bfe_u32 v155, v168, 6, 2
	v_lshlrev_b32_e32 v130, 6, v155
	v_and_b32_e32 v131, 15, v168
	v_lshl_or_b32 v130, v131, 2, v130
	v_add_u32_e32 v131, 0x1000, v130
	v_add_u32_e32 v131, 0x2000, v130
	v_add_u32_e32 v131, 0x3000, v130
	v_lshrrev_b32_e32 v130, 1, v155
	v_add_u32_e32 v130, s0, v130
	v_and_b32_e32 v130, 3, v130
	v_lshrrev_b32_e32 v131, 8, v168
	v_lshl_add_u32 v130, v131, 2, v130
	v_lshlrev_b32_e32 v130, 14, v130
	v_and_b32_e32 v131, 63, v168
	v_lshl_or_b32 v142, v131, 4, v130
	v_and_b32_e32 v131, 1, v155
	v_lshl_or_b32 v142, v131, 3, v142
	v_add_u32_e32 v0, 0x2000, v142
	global_load_dwordx2 v[198:199], v142, s[8:9] offset:2048
	global_load_dwordx2 v[200:201], v142, s[10:11] offset:2048
	global_load_dwordx2 v[202:203], v142, s[42:43] offset:2048
	global_load_dwordx2 v[204:205], v142, s[44:45] offset:2048
	global_load_dwordx2 v[206:207], v142, s[8:9] offset:3072
	global_load_dwordx2 v[208:209], v142, s[10:11] offset:3072
	global_load_dwordx2 v[210:211], v142, s[42:43] offset:3072
	global_load_dwordx2 v[212:213], v142, s[44:45] offset:3072
	global_load_dwordx2 v[214:215], v0, s[8:9] offset:0
	global_load_dwordx2 v[216:217], v0, s[10:11] offset:0
	global_load_dwordx2 v[218:219], v0, s[42:43] offset:0
	global_load_dwordx2 v[220:221], v0, s[44:45] offset:0
	global_load_dwordx2 v[222:223], v0, s[8:9] offset:1024
	global_load_dwordx2 v[224:225], v0, s[10:11] offset:1024
	global_load_dwordx2 v[226:227], v0, s[42:43] offset:1024
	global_load_dwordx2 v[228:229], v0, s[44:45] offset:1024
	global_load_dwordx2 v[182:183], v0, s[8:9] offset:2048
	global_load_dwordx2 v[184:185], v0, s[10:11] offset:2048
	global_load_dwordx2 v[186:187], v0, s[42:43] offset:2048
	global_load_dwordx2 v[188:189], v0, s[44:45] offset:2048
	global_load_dwordx2 v[190:191], v0, s[8:9] offset:3072
	global_load_dwordx2 v[192:193], v0, s[10:11] offset:3072
	global_load_dwordx2 v[194:195], v0, s[42:43] offset:3072
	global_load_dwordx2 v[196:197], v0, s[44:45] offset:3072
	s_waitcnt vmcnt(24)
	v_mul_f32_e32 v170, 0xbfb8aa3b, v170
	v_mul_f32_e32 v252, 0xbfb8aa3b, v252
	v_mul_f32_e32 v253, 0xbfb8aa3b, v253
	v_mul_f32_e32 v162, 0xbfb8aa3b, v162
	v_fmamk_f32 v158, v158, 0xbfb8aa3b, v170
	v_exp_f32_e32 v158, v158
	v_fmamk_f32 v159, v159, 0xbfb8aa3b, v170
	v_exp_f32_e32 v159, v159
	v_fmamk_f32 v160, v160, 0xbfb8aa3b, v170
	v_exp_f32_e32 v160, v160
	v_fmamk_f32 v161, v161, 0xbfb8aa3b, v170
	v_exp_f32_e32 v161, v161
	v_fmamk_f32 v150, v150, 0xbfb8aa3b, v252
	v_exp_f32_e32 v150, v150
	v_fmamk_f32 v151, v151, 0xbfb8aa3b, v252
	v_exp_f32_e32 v151, v151
	v_fmamk_f32 v152, v152, 0xbfb8aa3b, v252
	v_exp_f32_e32 v152, v152
	v_fmamk_f32 v153, v153, 0xbfb8aa3b, v252
	v_exp_f32_e32 v153, v153
	v_fmamk_f32 v110, v110, 0xbfb8aa3b, v253
	v_exp_f32_e32 v110, v110
	v_fmamk_f32 v111, v111, 0xbfb8aa3b, v253
	v_exp_f32_e32 v111, v111
	v_fmamk_f32 v112, v112, 0xbfb8aa3b, v253
	v_exp_f32_e32 v112, v112
	v_fmamk_f32 v113, v113, 0xbfb8aa3b, v253
	v_exp_f32_e32 v113, v113
	v_fmamk_f32 v106, v106, 0xbfb8aa3b, v162
	v_exp_f32_e32 v106, v106
	v_fmamk_f32 v107, v107, 0xbfb8aa3b, v162
	v_exp_f32_e32 v107, v107
	v_fmamk_f32 v108, v108, 0xbfb8aa3b, v162
	v_exp_f32_e32 v108, v108
	v_fmamk_f32 v109, v109, 0xbfb8aa3b, v162
	v_exp_f32_e32 v109, v109
	v_add_f32_e32 v158, 1.0, v158
	v_add_f32_e32 v159, 1.0, v159
	v_lshlrev_b32_e32 v156, 16, v230
	v_and_b32_e32 v157, 0xffff0000, v230
	v_rcp_f32_e32 v158, v158
	v_rcp_f32_e32 v159, v159
	v_add_f32_e32 v160, 1.0, v160
	v_add_f32_e32 v161, 1.0, v161
	v_lshlrev_b32_e32 v164, 16, v231
	v_and_b32_e32 v165, 0xffff0000, v231
	v_rcp_f32_e32 v160, v160
	v_rcp_f32_e32 v161, v161
	v_mul_f32_e32 v158, v158, v156
	v_mul_f32_e32 v159, v159, v157
	v_mul_f32_e32 v160, v160, v164
	v_mul_f32_e32 v161, v161, v165
	v_add_f32_e32 v150, 1.0, v150
	v_add_f32_e32 v151, 1.0, v151
	v_lshlrev_b32_e32 v156, 16, v232
	v_and_b32_e32 v157, 0xffff0000, v232
	v_rcp_f32_e32 v150, v150
	v_rcp_f32_e32 v151, v151
	v_add_f32_e32 v152, 1.0, v152
	v_add_f32_e32 v153, 1.0, v153
	v_lshlrev_b32_e32 v164, 16, v233
	v_and_b32_e32 v165, 0xffff0000, v233
	v_rcp_f32_e32 v152, v152
	v_rcp_f32_e32 v153, v153
	v_fmac_f32_e32 v158, v150, v156
	v_fmac_f32_e32 v159, v151, v157
	v_fmac_f32_e32 v160, v152, v164
	v_fmac_f32_e32 v161, v153, v165
	v_add_f32_e32 v110, 1.0, v110
	v_add_f32_e32 v111, 1.0, v111
	v_lshlrev_b32_e32 v156, 16, v234
	v_and_b32_e32 v157, 0xffff0000, v234
	v_rcp_f32_e32 v110, v110
	v_rcp_f32_e32 v111, v111
	v_add_f32_e32 v112, 1.0, v112
	v_add_f32_e32 v113, 1.0, v113
	v_lshlrev_b32_e32 v164, 16, v235
	v_and_b32_e32 v165, 0xffff0000, v235
	v_rcp_f32_e32 v112, v112
	v_rcp_f32_e32 v113, v113
	v_fmac_f32_e32 v158, v110, v156
	v_fmac_f32_e32 v159, v111, v157
	v_fmac_f32_e32 v160, v112, v164
	v_fmac_f32_e32 v161, v113, v165
	v_add_f32_e32 v106, 1.0, v106
	v_add_f32_e32 v107, 1.0, v107
	v_lshlrev_b32_e32 v156, 16, v236
	v_and_b32_e32 v157, 0xffff0000, v236
	v_rcp_f32_e32 v106, v106
	v_rcp_f32_e32 v107, v107
	v_add_f32_e32 v108, 1.0, v108
	v_add_f32_e32 v109, 1.0, v109
	v_lshlrev_b32_e32 v164, 16, v237
	v_and_b32_e32 v165, 0xffff0000, v237
	v_rcp_f32_e32 v108, v108
	v_rcp_f32_e32 v109, v109
	v_fmac_f32_e32 v158, v106, v156
	v_fmac_f32_e32 v159, v107, v157
	v_fmac_f32_e32 v160, v108, v164
	v_fmac_f32_e32 v161, v109, v165
	s_waitcnt vmcnt(24)
; DI float sigm(float x) { return 1.f / (1.f + __expf(-x)); }
; DI u32x4 pack8(const float* f) { u32x4 o; o.x = pack2(f[0], f[1]); o.y = pack2(f[2], f[3]); o.z = pack2(f[4], f[5]); o.w = pack2(f[6], f[7]); return o; }
; DI void gate_reg(PREF p, int l, int n, f32x4 (&acc)[2][2][4][2], int dt) {
;     ...
;   for (int ai = 0; ai < 2; ++ai)
; #pragma unroll
;     for (int bj = 0; bj < 2; ++bj) {
;       __builtin_amdgcn_sched_barrier(0);
;       u32x4 bn[4], pv[4];
; #pragma unroll
;       for (int m = 0; m < 4; ++m) {
;         bn[m] = sbn[((ai * 2 + bj) * 4 + m) * 64];
;         if (n > 0) pv[m] = ssum[((ai * 2 + bj) * 4 + m) * 64];
;       }
; #pragma unroll
;       for (int m = 0; m < 4; ++m) {
;         float b[8]; unpack8(bn[m], b);
;         float v[8];
; #pragma unroll
;         for (int nn = 0; nn < 2; ++nn)
; #pragma unroll
;           for (int j = 0; j < 4; ++j) v[nn * 4 + j] = sigm(acc[ai][bj][m][nn][j] + bias[bj][nn]) * b[nn * 4 + j];
;         if (n > 0) {
;           float o[8]; unpack8(pv[m], o);
; #pragma unroll
;           for (int e = 0; e < 8; ++e) v[e] += o[e];
;         }
;         if (n < 3) ssum[((ai * 2 + bj) * 4 + m) * 64] = pack8(v);
; #pragma unroll
;         for (int nn = 0; nn < 2; ++nn)
; #pragma unroll
;           for (int j = 0; j < 4; ++j) acc[ai][bj][m][nn][j] = v[nn * 4 + j];
;       }
;     }
	v_fmamk_f32 v146, v146, 0xbfb8aa3b, v170
	v_exp_f32_e32 v146, v146
	v_fmamk_f32 v147, v147, 0xbfb8aa3b, v170
	v_exp_f32_e32 v147, v147
	v_fmamk_f32 v148, v148, 0xbfb8aa3b, v170
	v_exp_f32_e32 v148, v148
	v_fmamk_f32 v149, v149, 0xbfb8aa3b, v170
	v_exp_f32_e32 v149, v149
	v_fmamk_f32 v138, v138, 0xbfb8aa3b, v252
	v_exp_f32_e32 v138, v138
	v_fmamk_f32 v139, v139, 0xbfb8aa3b, v252
	v_exp_f32_e32 v139, v139
	v_fmamk_f32 v140, v140, 0xbfb8aa3b, v252
	v_exp_f32_e32 v140, v140
	v_fmamk_f32 v141, v141, 0xbfb8aa3b, v252
	v_exp_f32_e32 v141, v141
	v_fmamk_f32 v102, v102, 0xbfb8aa3b, v253
	v_exp_f32_e32 v102, v102
	v_fmamk_f32 v103, v103, 0xbfb8aa3b, v253
	v_exp_f32_e32 v103, v103
	v_fmamk_f32 v104, v104, 0xbfb8aa3b, v253
	v_exp_f32_e32 v104, v104
	v_fmamk_f32 v105, v105, 0xbfb8aa3b, v253
	v_exp_f32_e32 v105, v105
	v_fmamk_f32 v98, v98, 0xbfb8aa3b, v162
	v_exp_f32_e32 v98, v98
	v_fmamk_f32 v99, v99, 0xbfb8aa3b, v162
	v_exp_f32_e32 v99, v99
	v_fmamk_f32 v100, v100, 0xbfb8aa3b, v162
	v_exp_f32_e32 v100, v100
	v_fmamk_f32 v101, v101, 0xbfb8aa3b, v162
	v_exp_f32_e32 v101, v101
	v_add_f32_e32 v146, 1.0, v146
	v_add_f32_e32 v147, 1.0, v147
	v_lshlrev_b32_e32 v156, 16, v238
	v_and_b32_e32 v157, 0xffff0000, v238
	v_rcp_f32_e32 v146, v146
	v_rcp_f32_e32 v147, v147
	v_add_f32_e32 v148, 1.0, v148
	v_add_f32_e32 v149, 1.0, v149
	v_lshlrev_b32_e32 v164, 16, v239
	v_and_b32_e32 v165, 0xffff0000, v239
	v_rcp_f32_e32 v148, v148
	v_rcp_f32_e32 v149, v149
	v_mul_f32_e32 v146, v146, v156
	v_mul_f32_e32 v147, v147, v157
	v_mul_f32_e32 v148, v148, v164
	v_mul_f32_e32 v149, v149, v165
	v_add_f32_e32 v138, 1.0, v138
	v_add_f32_e32 v139, 1.0, v139
	v_lshlrev_b32_e32 v156, 16, v240
	v_and_b32_e32 v157, 0xffff0000, v240
	v_rcp_f32_e32 v138, v138
	v_rcp_f32_e32 v139, v139
	v_add_f32_e32 v140, 1.0, v140
	v_add_f32_e32 v141, 1.0, v141
	v_lshlrev_b32_e32 v164, 16, v241
	v_and_b32_e32 v165, 0xffff0000, v241
	v_rcp_f32_e32 v140, v140
	v_rcp_f32_e32 v141, v141
	v_fmac_f32_e32 v146, v138, v156
	v_fmac_f32_e32 v147, v139, v157
	v_fmac_f32_e32 v148, v140, v164
	v_fmac_f32_e32 v149, v141, v165
	v_add_f32_e32 v102, 1.0, v102
	v_add_f32_e32 v103, 1.0, v103
	v_lshlrev_b32_e32 v156, 16, v242
	v_and_b32_e32 v157, 0xffff0000, v242
	v_rcp_f32_e32 v102, v102
	v_rcp_f32_e32 v103, v103
	v_add_f32_e32 v104, 1.0, v104
	v_add_f32_e32 v105, 1.0, v105
	v_lshlrev_b32_e32 v164, 16, v243
	v_and_b32_e32 v165, 0xffff0000, v243
	v_rcp_f32_e32 v104, v104
	v_rcp_f32_e32 v105, v105
	v_fmac_f32_e32 v146, v102, v156
	v_fmac_f32_e32 v147, v103, v157
	v_fmac_f32_e32 v148, v104, v164
	v_fmac_f32_e32 v149, v105, v165
	v_add_f32_e32 v98, 1.0, v98
	v_add_f32_e32 v99, 1.0, v99
	v_lshlrev_b32_e32 v156, 16, v244
	v_and_b32_e32 v157, 0xffff0000, v244
	v_rcp_f32_e32 v98, v98
	v_rcp_f32_e32 v99, v99
	v_add_f32_e32 v100, 1.0, v100
	v_add_f32_e32 v101, 1.0, v101
	v_lshlrev_b32_e32 v164, 16, v245
	v_and_b32_e32 v165, 0xffff0000, v245
	v_rcp_f32_e32 v100, v100
	v_rcp_f32_e32 v101, v101
	v_fmac_f32_e32 v146, v98, v156
	v_fmac_f32_e32 v147, v99, v157
	v_fmac_f32_e32 v148, v100, v164
	v_fmac_f32_e32 v149, v101, v165
	s_waitcnt vmcnt(20)
	v_fmamk_f32 v134, v134, 0xbfb8aa3b, v170
	v_exp_f32_e32 v134, v134
	v_fmamk_f32 v135, v135, 0xbfb8aa3b, v170
	v_exp_f32_e32 v135, v135
	v_fmamk_f32 v136, v136, 0xbfb8aa3b, v170
	v_exp_f32_e32 v136, v136
	v_fmamk_f32 v137, v137, 0xbfb8aa3b, v170
	v_exp_f32_e32 v137, v137
	v_fmamk_f32 v126, v126, 0xbfb8aa3b, v252
	v_exp_f32_e32 v126, v126
	v_fmamk_f32 v127, v127, 0xbfb8aa3b, v252
	v_exp_f32_e32 v127, v127
	v_fmamk_f32 v128, v128, 0xbfb8aa3b, v252
	v_exp_f32_e32 v128, v128
	v_fmamk_f32 v129, v129, 0xbfb8aa3b, v252
	v_exp_f32_e32 v129, v129
	v_fmamk_f32 v94, v94, 0xbfb8aa3b, v253
	v_exp_f32_e32 v94, v94
	v_fmamk_f32 v95, v95, 0xbfb8aa3b, v253
	v_exp_f32_e32 v95, v95
	v_fmamk_f32 v96, v96, 0xbfb8aa3b, v253
	v_exp_f32_e32 v96, v96
	v_fmamk_f32 v97, v97, 0xbfb8aa3b, v253
	v_exp_f32_e32 v97, v97
	v_fmamk_f32 v90, v90, 0xbfb8aa3b, v162
	v_exp_f32_e32 v90, v90
	v_fmamk_f32 v91, v91, 0xbfb8aa3b, v162
	v_exp_f32_e32 v91, v91
	v_fmamk_f32 v92, v92, 0xbfb8aa3b, v162
	v_exp_f32_e32 v92, v92
	v_fmamk_f32 v93, v93, 0xbfb8aa3b, v162
	v_exp_f32_e32 v93, v93
	v_add_f32_e32 v134, 1.0, v134
	v_add_f32_e32 v135, 1.0, v135
	v_lshlrev_b32_e32 v156, 16, v198
	v_and_b32_e32 v157, 0xffff0000, v198
	v_rcp_f32_e32 v134, v134
	v_rcp_f32_e32 v135, v135
	v_add_f32_e32 v136, 1.0, v136
	v_add_f32_e32 v137, 1.0, v137
	v_lshlrev_b32_e32 v164, 16, v199
	v_and_b32_e32 v165, 0xffff0000, v199
	v_rcp_f32_e32 v136, v136
	v_rcp_f32_e32 v137, v137
	v_mul_f32_e32 v134, v134, v156
	v_mul_f32_e32 v135, v135, v157
	v_mul_f32_e32 v136, v136, v164
	v_mul_f32_e32 v137, v137, v165
	v_add_f32_e32 v126, 1.0, v126
	v_add_f32_e32 v127, 1.0, v127
	v_lshlrev_b32_e32 v156, 16, v200
	v_and_b32_e32 v157, 0xffff0000, v200
	v_rcp_f32_e32 v126, v126
	v_rcp_f32_e32 v127, v127
	v_add_f32_e32 v128, 1.0, v128
	v_add_f32_e32 v129, 1.0, v129
	v_lshlrev_b32_e32 v164, 16, v201
	v_and_b32_e32 v165, 0xffff0000, v201
	v_rcp_f32_e32 v128, v128
	v_rcp_f32_e32 v129, v129
	v_fmac_f32_e32 v134, v126, v156
	v_fmac_f32_e32 v135, v127, v157
	v_fmac_f32_e32 v136, v128, v164
	v_fmac_f32_e32 v137, v129, v165
	v_add_f32_e32 v94, 1.0, v94
	v_add_f32_e32 v95, 1.0, v95
	v_lshlrev_b32_e32 v156, 16, v202
	v_and_b32_e32 v157, 0xffff0000, v202
	v_rcp_f32_e32 v94, v94
	v_rcp_f32_e32 v95, v95
	v_add_f32_e32 v96, 1.0, v96
	v_add_f32_e32 v97, 1.0, v97
	v_lshlrev_b32_e32 v164, 16, v203
	v_and_b32_e32 v165, 0xffff0000, v203
	v_rcp_f32_e32 v96, v96
	v_rcp_f32_e32 v97, v97
	v_fmac_f32_e32 v134, v94, v156
	v_fmac_f32_e32 v135, v95, v157
	v_fmac_f32_e32 v136, v96, v164
	v_fmac_f32_e32 v137, v97, v165
	v_add_f32_e32 v90, 1.0, v90
	v_add_f32_e32 v91, 1.0, v91
	v_lshlrev_b32_e32 v156, 16, v204
	v_and_b32_e32 v157, 0xffff0000, v204
	v_rcp_f32_e32 v90, v90
	v_rcp_f32_e32 v91, v91
	v_add_f32_e32 v92, 1.0, v92
	v_add_f32_e32 v93, 1.0, v93
	v_lshlrev_b32_e32 v164, 16, v205
	v_and_b32_e32 v165, 0xffff0000, v205
	v_rcp_f32_e32 v92, v92
	v_rcp_f32_e32 v93, v93
	v_fmac_f32_e32 v134, v90, v156
	v_fmac_f32_e32 v135, v91, v157
	v_fmac_f32_e32 v136, v92, v164
	v_fmac_f32_e32 v137, v93, v165
	s_waitcnt vmcnt(16)
; DI float sigm(float x) { return 1.f / (1.f + __expf(-x)); }
; DI u32x4 pack8(const float* f) { u32x4 o; o.x = pack2(f[0], f[1]); o.y = pack2(f[2], f[3]); o.z = pack2(f[4], f[5]); o.w = pack2(f[6], f[7]); return o; }
; DI void gate_reg(PREF p, int l, int n, f32x4 (&acc)[2][2][4][2], int dt) {
;     ...
;   for (int ai = 0; ai < 2; ++ai)
; #pragma unroll
;     for (int bj = 0; bj < 2; ++bj) {
;       __builtin_amdgcn_sched_barrier(0);
;       u32x4 bn[4], pv[4];
; #pragma unroll
;       for (int m = 0; m < 4; ++m) {
;         bn[m] = sbn[((ai * 2 + bj) * 4 + m) * 64];
;         if (n > 0) pv[m] = ssum[((ai * 2 + bj) * 4 + m) * 64];
;       }
; #pragma unroll
;       for (int m = 0; m < 4; ++m) {
;         float b[8]; unpack8(bn[m], b);
;         float v[8];
; #pragma unroll
;         for (int nn = 0; nn < 2; ++nn)
; #pragma unroll
;           for (int j = 0; j < 4; ++j) v[nn * 4 + j] = sigm(acc[ai][bj][m][nn][j] + bias[bj][nn]) * b[nn * 4 + j];
;         if (n > 0) {
;           float o[8]; unpack8(pv[m], o);
; #pragma unroll
;           for (int e = 0; e < 8; ++e) v[e] += o[e];
;         }
;         if (n < 3) ssum[((ai * 2 + bj) * 4 + m) * 64] = pack8(v);
; #pragma unroll
;         for (int nn = 0; nn < 2; ++nn)
; #pragma unroll
;           for (int j = 0; j < 4; ++j) acc[ai][bj][m][nn][j] = v[nn * 4 + j];
;       }
;     }
	v_fmamk_f32 v122, v122, 0xbfb8aa3b, v170
	v_exp_f32_e32 v122, v122
	v_fmamk_f32 v123, v123, 0xbfb8aa3b, v170
	v_exp_f32_e32 v123, v123
	v_fmamk_f32 v124, v124, 0xbfb8aa3b, v170
	v_exp_f32_e32 v124, v124
	v_fmamk_f32 v125, v125, 0xbfb8aa3b, v170
	v_exp_f32_e32 v125, v125
	v_fmamk_f32 v114, v114, 0xbfb8aa3b, v252
	v_exp_f32_e32 v114, v114
	v_fmamk_f32 v115, v115, 0xbfb8aa3b, v252
	v_exp_f32_e32 v115, v115
	v_fmamk_f32 v116, v116, 0xbfb8aa3b, v252
	v_exp_f32_e32 v116, v116
	v_fmamk_f32 v117, v117, 0xbfb8aa3b, v252
	v_exp_f32_e32 v117, v117
	v_fmamk_f32 v86, v86, 0xbfb8aa3b, v253
	v_exp_f32_e32 v86, v86
	v_fmamk_f32 v87, v87, 0xbfb8aa3b, v253
	v_exp_f32_e32 v87, v87
	v_fmamk_f32 v88, v88, 0xbfb8aa3b, v253
	v_exp_f32_e32 v88, v88
	v_fmamk_f32 v89, v89, 0xbfb8aa3b, v253
	v_exp_f32_e32 v89, v89
	v_fmamk_f32 v82, v82, 0xbfb8aa3b, v162
	v_exp_f32_e32 v82, v82
	v_fmamk_f32 v83, v83, 0xbfb8aa3b, v162
	v_exp_f32_e32 v83, v83
	v_fmamk_f32 v84, v84, 0xbfb8aa3b, v162
	v_exp_f32_e32 v84, v84
	v_fmamk_f32 v85, v85, 0xbfb8aa3b, v162
	v_exp_f32_e32 v85, v85
	v_add_f32_e32 v122, 1.0, v122
	v_add_f32_e32 v123, 1.0, v123
	v_lshlrev_b32_e32 v156, 16, v206
	v_and_b32_e32 v157, 0xffff0000, v206
	v_rcp_f32_e32 v122, v122
	v_rcp_f32_e32 v123, v123
	v_add_f32_e32 v124, 1.0, v124
	v_add_f32_e32 v125, 1.0, v125
	v_lshlrev_b32_e32 v164, 16, v207
	v_and_b32_e32 v165, 0xffff0000, v207
	v_rcp_f32_e32 v124, v124
	v_rcp_f32_e32 v125, v125
	v_mul_f32_e32 v122, v122, v156
	v_mul_f32_e32 v123, v123, v157
	v_mul_f32_e32 v124, v124, v164
	v_mul_f32_e32 v125, v125, v165
	v_add_f32_e32 v114, 1.0, v114
	v_add_f32_e32 v115, 1.0, v115
	v_lshlrev_b32_e32 v156, 16, v208
	v_and_b32_e32 v157, 0xffff0000, v208
	v_rcp_f32_e32 v114, v114
	v_rcp_f32_e32 v115, v115
	v_add_f32_e32 v116, 1.0, v116
	v_add_f32_e32 v117, 1.0, v117
	v_lshlrev_b32_e32 v164, 16, v209
	v_and_b32_e32 v165, 0xffff0000, v209
	v_rcp_f32_e32 v116, v116
	v_rcp_f32_e32 v117, v117
	v_fmac_f32_e32 v122, v114, v156
	v_fmac_f32_e32 v123, v115, v157
	v_fmac_f32_e32 v124, v116, v164
	v_fmac_f32_e32 v125, v117, v165
	v_add_f32_e32 v86, 1.0, v86
	v_add_f32_e32 v87, 1.0, v87
	v_lshlrev_b32_e32 v156, 16, v210
	v_and_b32_e32 v157, 0xffff0000, v210
	v_rcp_f32_e32 v86, v86
	v_rcp_f32_e32 v87, v87
	v_add_f32_e32 v88, 1.0, v88
	v_add_f32_e32 v89, 1.0, v89
	v_lshlrev_b32_e32 v164, 16, v211
	v_and_b32_e32 v165, 0xffff0000, v211
	v_rcp_f32_e32 v88, v88
	v_rcp_f32_e32 v89, v89
	v_fmac_f32_e32 v122, v86, v156
	v_fmac_f32_e32 v123, v87, v157
	v_fmac_f32_e32 v124, v88, v164
	v_fmac_f32_e32 v125, v89, v165
	v_add_f32_e32 v82, 1.0, v82
	v_add_f32_e32 v83, 1.0, v83
	v_lshlrev_b32_e32 v156, 16, v212
	v_and_b32_e32 v157, 0xffff0000, v212
	v_rcp_f32_e32 v82, v82
	v_rcp_f32_e32 v83, v83
	v_add_f32_e32 v84, 1.0, v84
	v_add_f32_e32 v85, 1.0, v85
	v_lshlrev_b32_e32 v164, 16, v213
	v_and_b32_e32 v165, 0xffff0000, v213
	v_rcp_f32_e32 v84, v84
	v_rcp_f32_e32 v85, v85
	v_fmac_f32_e32 v122, v82, v156
	v_fmac_f32_e32 v123, v83, v157
	v_fmac_f32_e32 v124, v84, v164
	v_fmac_f32_e32 v125, v85, v165
	s_waitcnt vmcnt(12)
	v_fmamk_f32 v78, v78, 0xbfb8aa3b, v170
	v_exp_f32_e32 v78, v78
	v_fmamk_f32 v79, v79, 0xbfb8aa3b, v170
	v_exp_f32_e32 v79, v79
	v_fmamk_f32 v80, v80, 0xbfb8aa3b, v170
	v_exp_f32_e32 v80, v80
	v_fmamk_f32 v81, v81, 0xbfb8aa3b, v170
	v_exp_f32_e32 v81, v81
	v_fmamk_f32 v74, v74, 0xbfb8aa3b, v252
	v_exp_f32_e32 v74, v74
	v_fmamk_f32 v75, v75, 0xbfb8aa3b, v252
	v_exp_f32_e32 v75, v75
	v_fmamk_f32 v76, v76, 0xbfb8aa3b, v252
	v_exp_f32_e32 v76, v76
	v_fmamk_f32 v77, v77, 0xbfb8aa3b, v252
	v_exp_f32_e32 v77, v77
	v_fmamk_f32 v46, v46, 0xbfb8aa3b, v253
	v_exp_f32_e32 v46, v46
	v_fmamk_f32 v47, v47, 0xbfb8aa3b, v253
	v_exp_f32_e32 v47, v47
	v_fmamk_f32 v48, v48, 0xbfb8aa3b, v253
	v_exp_f32_e32 v48, v48
	v_fmamk_f32 v49, v49, 0xbfb8aa3b, v253
	v_exp_f32_e32 v49, v49
	v_fmamk_f32 v38, v38, 0xbfb8aa3b, v162
	v_exp_f32_e32 v38, v38
	v_fmamk_f32 v39, v39, 0xbfb8aa3b, v162
	v_exp_f32_e32 v39, v39
	v_fmamk_f32 v40, v40, 0xbfb8aa3b, v162
	v_exp_f32_e32 v40, v40
	v_fmamk_f32 v41, v41, 0xbfb8aa3b, v162
	v_exp_f32_e32 v41, v41
	v_add_f32_e32 v78, 1.0, v78
	v_add_f32_e32 v79, 1.0, v79
	v_lshlrev_b32_e32 v156, 16, v214
	v_and_b32_e32 v157, 0xffff0000, v214
	v_rcp_f32_e32 v78, v78
	v_rcp_f32_e32 v79, v79
	v_add_f32_e32 v80, 1.0, v80
	v_add_f32_e32 v81, 1.0, v81
	v_lshlrev_b32_e32 v164, 16, v215
	v_and_b32_e32 v165, 0xffff0000, v215
	v_rcp_f32_e32 v80, v80
	v_rcp_f32_e32 v81, v81
	v_mul_f32_e32 v78, v78, v156
	v_mul_f32_e32 v79, v79, v157
	v_mul_f32_e32 v80, v80, v164
	v_mul_f32_e32 v81, v81, v165
	v_add_f32_e32 v74, 1.0, v74
	v_add_f32_e32 v75, 1.0, v75
	v_lshlrev_b32_e32 v156, 16, v216
	v_and_b32_e32 v157, 0xffff0000, v216
	v_rcp_f32_e32 v74, v74
	v_rcp_f32_e32 v75, v75
	v_add_f32_e32 v76, 1.0, v76
	v_add_f32_e32 v77, 1.0, v77
	v_lshlrev_b32_e32 v164, 16, v217
	v_and_b32_e32 v165, 0xffff0000, v217
	v_rcp_f32_e32 v76, v76
	v_rcp_f32_e32 v77, v77
	v_fmac_f32_e32 v78, v74, v156
	v_fmac_f32_e32 v79, v75, v157
	v_fmac_f32_e32 v80, v76, v164
	v_fmac_f32_e32 v81, v77, v165
	v_add_f32_e32 v46, 1.0, v46
	v_add_f32_e32 v47, 1.0, v47
	v_lshlrev_b32_e32 v156, 16, v218
	v_and_b32_e32 v157, 0xffff0000, v218
	v_rcp_f32_e32 v46, v46
	v_rcp_f32_e32 v47, v47
	v_add_f32_e32 v48, 1.0, v48
	v_add_f32_e32 v49, 1.0, v49
	v_lshlrev_b32_e32 v164, 16, v219
	v_and_b32_e32 v165, 0xffff0000, v219
	v_rcp_f32_e32 v48, v48
	v_rcp_f32_e32 v49, v49
	v_fmac_f32_e32 v78, v46, v156
	v_fmac_f32_e32 v79, v47, v157
	v_fmac_f32_e32 v80, v48, v164
	v_fmac_f32_e32 v81, v49, v165
	v_add_f32_e32 v38, 1.0, v38
	v_add_f32_e32 v39, 1.0, v39
	v_lshlrev_b32_e32 v156, 16, v220
	v_and_b32_e32 v157, 0xffff0000, v220
	v_rcp_f32_e32 v38, v38
	v_rcp_f32_e32 v39, v39
	v_add_f32_e32 v40, 1.0, v40
	v_add_f32_e32 v41, 1.0, v41
	v_lshlrev_b32_e32 v164, 16, v221
	v_and_b32_e32 v165, 0xffff0000, v221
	v_rcp_f32_e32 v40, v40
	v_rcp_f32_e32 v41, v41
	v_fmac_f32_e32 v78, v38, v156
	v_fmac_f32_e32 v79, v39, v157
	v_fmac_f32_e32 v80, v40, v164
	v_fmac_f32_e32 v81, v41, v165
	s_waitcnt vmcnt(8)
; DI float sigm(float x) { return 1.f / (1.f + __expf(-x)); }
; DI u32x4 pack8(const float* f) { u32x4 o; o.x = pack2(f[0], f[1]); o.y = pack2(f[2], f[3]); o.z = pack2(f[4], f[5]); o.w = pack2(f[6], f[7]); return o; }
; DI void gate_reg(PREF p, int l, int n, f32x4 (&acc)[2][2][4][2], int dt) {
;     ...
;   for (int ai = 0; ai < 2; ++ai)
; #pragma unroll
;     for (int bj = 0; bj < 2; ++bj) {
;       __builtin_amdgcn_sched_barrier(0);
;       u32x4 bn[4], pv[4];
; #pragma unroll
;       for (int m = 0; m < 4; ++m) {
;         bn[m] = sbn[((ai * 2 + bj) * 4 + m) * 64];
;         if (n > 0) pv[m] = ssum[((ai * 2 + bj) * 4 + m) * 64];
;       }
; #pragma unroll
;       for (int m = 0; m < 4; ++m) {
;         float b[8]; unpack8(bn[m], b);
;         float v[8];
; #pragma unroll
;         for (int nn = 0; nn < 2; ++nn)
; #pragma unroll
;           for (int j = 0; j < 4; ++j) v[nn * 4 + j] = sigm(acc[ai][bj][m][nn][j] + bias[bj][nn]) * b[nn * 4 + j];
;         if (n > 0) {
;           float o[8]; unpack8(pv[m], o);
; #pragma unroll
;           for (int e = 0; e < 8; ++e) v[e] += o[e];
;         }
;         if (n < 3) ssum[((ai * 2 + bj) * 4 + m) * 64] = pack8(v);
; #pragma unroll
;         for (int nn = 0; nn < 2; ++nn)
; #pragma unroll
;           for (int j = 0; j < 4; ++j) acc[ai][bj][m][nn][j] = v[nn * 4 + j];
;       }
;     }
	v_fmamk_f32 v70, v70, 0xbfb8aa3b, v170
	v_exp_f32_e32 v70, v70
	v_fmamk_f32 v71, v71, 0xbfb8aa3b, v170
	v_exp_f32_e32 v71, v71
	v_fmamk_f32 v72, v72, 0xbfb8aa3b, v170
	v_exp_f32_e32 v72, v72
	v_fmamk_f32 v73, v73, 0xbfb8aa3b, v170
	v_exp_f32_e32 v73, v73
	v_fmamk_f32 v66, v66, 0xbfb8aa3b, v252
	v_exp_f32_e32 v66, v66
	v_fmamk_f32 v67, v67, 0xbfb8aa3b, v252
	v_exp_f32_e32 v67, v67
	v_fmamk_f32 v68, v68, 0xbfb8aa3b, v252
	v_exp_f32_e32 v68, v68
	v_fmamk_f32 v69, v69, 0xbfb8aa3b, v252
	v_exp_f32_e32 v69, v69
	v_fmamk_f32 v34, v34, 0xbfb8aa3b, v253
	v_exp_f32_e32 v34, v34
	v_fmamk_f32 v35, v35, 0xbfb8aa3b, v253
	v_exp_f32_e32 v35, v35
	v_fmamk_f32 v36, v36, 0xbfb8aa3b, v253
	v_exp_f32_e32 v36, v36
	v_fmamk_f32 v37, v37, 0xbfb8aa3b, v253
	v_exp_f32_e32 v37, v37
	v_fmamk_f32 v26, v26, 0xbfb8aa3b, v162
	v_exp_f32_e32 v26, v26
	v_fmamk_f32 v27, v27, 0xbfb8aa3b, v162
	v_exp_f32_e32 v27, v27
	v_fmamk_f32 v28, v28, 0xbfb8aa3b, v162
	v_exp_f32_e32 v28, v28
	v_fmamk_f32 v29, v29, 0xbfb8aa3b, v162
	v_exp_f32_e32 v29, v29
	v_add_f32_e32 v70, 1.0, v70
	v_add_f32_e32 v71, 1.0, v71
	v_lshlrev_b32_e32 v156, 16, v222
	v_and_b32_e32 v157, 0xffff0000, v222
	v_rcp_f32_e32 v70, v70
	v_rcp_f32_e32 v71, v71
	v_add_f32_e32 v72, 1.0, v72
	v_add_f32_e32 v73, 1.0, v73
	v_lshlrev_b32_e32 v164, 16, v223
	v_and_b32_e32 v165, 0xffff0000, v223
	v_rcp_f32_e32 v72, v72
	v_rcp_f32_e32 v73, v73
	v_mul_f32_e32 v70, v70, v156
	v_mul_f32_e32 v71, v71, v157
	v_mul_f32_e32 v72, v72, v164
	v_mul_f32_e32 v73, v73, v165
	v_add_f32_e32 v66, 1.0, v66
	v_add_f32_e32 v67, 1.0, v67
	v_lshlrev_b32_e32 v156, 16, v224
	v_and_b32_e32 v157, 0xffff0000, v224
	v_rcp_f32_e32 v66, v66
	v_rcp_f32_e32 v67, v67
	v_add_f32_e32 v68, 1.0, v68
	v_add_f32_e32 v69, 1.0, v69
	v_lshlrev_b32_e32 v164, 16, v225
	v_and_b32_e32 v165, 0xffff0000, v225
	v_rcp_f32_e32 v68, v68
	v_rcp_f32_e32 v69, v69
	v_fmac_f32_e32 v70, v66, v156
	v_fmac_f32_e32 v71, v67, v157
	v_fmac_f32_e32 v72, v68, v164
	v_fmac_f32_e32 v73, v69, v165
	v_add_f32_e32 v34, 1.0, v34
	v_add_f32_e32 v35, 1.0, v35
	v_lshlrev_b32_e32 v156, 16, v226
	v_and_b32_e32 v157, 0xffff0000, v226
	v_rcp_f32_e32 v34, v34
	v_rcp_f32_e32 v35, v35
	v_add_f32_e32 v36, 1.0, v36
	v_add_f32_e32 v37, 1.0, v37
	v_lshlrev_b32_e32 v164, 16, v227
	v_and_b32_e32 v165, 0xffff0000, v227
	v_rcp_f32_e32 v36, v36
	v_rcp_f32_e32 v37, v37
	v_fmac_f32_e32 v70, v34, v156
	v_fmac_f32_e32 v71, v35, v157
	v_fmac_f32_e32 v72, v36, v164
	v_fmac_f32_e32 v73, v37, v165
	v_add_f32_e32 v26, 1.0, v26
	v_add_f32_e32 v27, 1.0, v27
	v_lshlrev_b32_e32 v156, 16, v228
	v_and_b32_e32 v157, 0xffff0000, v228
	v_rcp_f32_e32 v26, v26
	v_rcp_f32_e32 v27, v27
	v_add_f32_e32 v28, 1.0, v28
	v_add_f32_e32 v29, 1.0, v29
	v_lshlrev_b32_e32 v164, 16, v229
	v_and_b32_e32 v165, 0xffff0000, v229
	v_rcp_f32_e32 v28, v28
	v_rcp_f32_e32 v29, v29
	v_fmac_f32_e32 v70, v26, v156
	v_fmac_f32_e32 v71, v27, v157
	v_fmac_f32_e32 v72, v28, v164
	v_fmac_f32_e32 v73, v29, v165
	s_waitcnt vmcnt(4)
	v_fmamk_f32 v62, v62, 0xbfb8aa3b, v170
	v_exp_f32_e32 v62, v62
	v_fmamk_f32 v63, v63, 0xbfb8aa3b, v170
	v_exp_f32_e32 v63, v63
	v_fmamk_f32 v64, v64, 0xbfb8aa3b, v170
	v_exp_f32_e32 v64, v64
	v_fmamk_f32 v65, v65, 0xbfb8aa3b, v170
	v_exp_f32_e32 v65, v65
	v_fmamk_f32 v58, v58, 0xbfb8aa3b, v252
	v_exp_f32_e32 v58, v58
	v_fmamk_f32 v59, v59, 0xbfb8aa3b, v252
	v_exp_f32_e32 v59, v59
	v_fmamk_f32 v60, v60, 0xbfb8aa3b, v252
	v_exp_f32_e32 v60, v60
	v_fmamk_f32 v61, v61, 0xbfb8aa3b, v252
	v_exp_f32_e32 v61, v61
	v_fmamk_f32 v22, v22, 0xbfb8aa3b, v253
	v_exp_f32_e32 v22, v22
	v_fmamk_f32 v23, v23, 0xbfb8aa3b, v253
	v_exp_f32_e32 v23, v23
	v_fmamk_f32 v24, v24, 0xbfb8aa3b, v253
	v_exp_f32_e32 v24, v24
	v_fmamk_f32 v25, v25, 0xbfb8aa3b, v253
	v_exp_f32_e32 v25, v25
	v_fmamk_f32 v14, v14, 0xbfb8aa3b, v162
	v_exp_f32_e32 v14, v14
	v_fmamk_f32 v15, v15, 0xbfb8aa3b, v162
	v_exp_f32_e32 v15, v15
	v_fmamk_f32 v16, v16, 0xbfb8aa3b, v162
	v_exp_f32_e32 v16, v16
	v_fmamk_f32 v17, v17, 0xbfb8aa3b, v162
	v_exp_f32_e32 v17, v17
	v_add_f32_e32 v62, 1.0, v62
	v_add_f32_e32 v63, 1.0, v63
	v_lshlrev_b32_e32 v156, 16, v182
	v_and_b32_e32 v157, 0xffff0000, v182
	v_rcp_f32_e32 v62, v62
	v_rcp_f32_e32 v63, v63
	v_add_f32_e32 v64, 1.0, v64
	v_add_f32_e32 v65, 1.0, v65
	v_lshlrev_b32_e32 v164, 16, v183
	v_and_b32_e32 v165, 0xffff0000, v183
	v_rcp_f32_e32 v64, v64
	v_rcp_f32_e32 v65, v65
	v_mul_f32_e32 v62, v62, v156
	v_mul_f32_e32 v63, v63, v157
	v_mul_f32_e32 v64, v64, v164
	v_mul_f32_e32 v65, v65, v165
	v_add_f32_e32 v58, 1.0, v58
	v_add_f32_e32 v59, 1.0, v59
	v_lshlrev_b32_e32 v156, 16, v184
	v_and_b32_e32 v157, 0xffff0000, v184
	v_rcp_f32_e32 v58, v58
	v_rcp_f32_e32 v59, v59
	v_add_f32_e32 v60, 1.0, v60
	v_add_f32_e32 v61, 1.0, v61
	v_lshlrev_b32_e32 v164, 16, v185
	v_and_b32_e32 v165, 0xffff0000, v185
	v_rcp_f32_e32 v60, v60
	v_rcp_f32_e32 v61, v61
	v_fmac_f32_e32 v62, v58, v156
	v_fmac_f32_e32 v63, v59, v157
	v_fmac_f32_e32 v64, v60, v164
	v_fmac_f32_e32 v65, v61, v165
	v_add_f32_e32 v22, 1.0, v22
	v_add_f32_e32 v23, 1.0, v23
	v_lshlrev_b32_e32 v156, 16, v186
	v_and_b32_e32 v157, 0xffff0000, v186
	v_rcp_f32_e32 v22, v22
	v_rcp_f32_e32 v23, v23
	v_add_f32_e32 v24, 1.0, v24
	v_add_f32_e32 v25, 1.0, v25
	v_lshlrev_b32_e32 v164, 16, v187
	v_and_b32_e32 v165, 0xffff0000, v187
	v_rcp_f32_e32 v24, v24
	v_rcp_f32_e32 v25, v25
	v_fmac_f32_e32 v62, v22, v156
	v_fmac_f32_e32 v63, v23, v157
	v_fmac_f32_e32 v64, v24, v164
	v_fmac_f32_e32 v65, v25, v165
	v_add_f32_e32 v14, 1.0, v14
	v_add_f32_e32 v15, 1.0, v15
	v_lshlrev_b32_e32 v156, 16, v188
	v_and_b32_e32 v157, 0xffff0000, v188
	v_rcp_f32_e32 v14, v14
	v_rcp_f32_e32 v15, v15
	v_add_f32_e32 v16, 1.0, v16
	v_add_f32_e32 v17, 1.0, v17
	v_lshlrev_b32_e32 v164, 16, v189
	v_and_b32_e32 v165, 0xffff0000, v189
	v_rcp_f32_e32 v16, v16
	v_rcp_f32_e32 v17, v17
	v_fmac_f32_e32 v62, v14, v156
	v_fmac_f32_e32 v63, v15, v157
	v_fmac_f32_e32 v64, v16, v164
	v_fmac_f32_e32 v65, v17, v165
	s_waitcnt vmcnt(0)
; DI int vbid() { return (int)blockIdx.x * 2 + half_(); }
; DI int vgrid() { return (int)gridDim.x * 2; }
; DI float sigm(float x) { return 1.f / (1.f + __expf(-x)); }
; DI u32x4 pack8(const float* f) { u32x4 o; o.x = pack2(f[0], f[1]); o.y = pack2(f[2], f[3]); o.z = pack2(f[4], f[5]); o.w = pack2(f[6], f[7]); return o; }
; DI void lds_barrier() { asm volatile("s_waitcnt lgkmcnt(0)\n\ts_barrier" ::: "memory"); }
; DI int tid512() { int t = threadIdx.x; asm volatile("" : "+v"(t)); return t; }
; template <int AI, int BJ>
; DI void stage_q(const f32x4 (&acc)[2][2][4][2], float* Cs) {
;   const int t = tid512(), wid = t >> 6, lane = t & 63, wr = wid >> 2, wc = wid & 3, fr = lane & 15, fq = lane >> 4;
;   lds_barrier();
; #pragma unroll
;   for (int m = 0; m < 4; ++m)
; #pragma unroll
;     for (int n = 0; n < 2; ++n)
; #pragma unroll
;       for (int j = 0; j < 4; ++j) Cs[(wr * 64 + m * 16 + fq * 4 + j) * CST + wc * 32 + n * 16 + fr] = acc[AI][BJ][m][n][j];
;   lds_barrier();
; }
; DI bool xcd_tile256(int k, int NT, int& m, int& n) {
;   const int x = blockIdx.x & 7, slots = gridDim.x >> 3;
;   const int idx = (int)(blockIdx.x >> 3) + slots * k;
;   if (idx >= 16 * NT) return false;
;   const int mg = idx / (8 * NT), rem = idx - mg * 8 * NT;
;   n = rem >> 3; m = x * 16 + mg * 8 + (rem & 7);
;   return true;
; }
; DI bool xcd_tile(int k, int NT, int& m, int& n) {
;   const int x = (vbid() >> 1) & 7, slots = vgrid() >> 3;
;   const int idx = (((vbid() >> 4) << 1) | (vbid() & 1)) + slots * k;
; DI void gate_reg(PREF p, int l, int n, f32x4 (&acc)[2][2][4][2], int dt) {
;     ...
;           for (int j = 0; j < 4; ++j) v[nn * 4 + j] = sigm(acc[ai][bj][m][nn][j] + bias[bj][nn]) * b[nn * 4 + j];
;         if (n > 0) {
;           float o[8]; unpack8(pv[m], o);
; #pragma unroll
;           for (int e = 0; e < 8; ++e) v[e] += o[e];
;         }
;         if (n < 3) ssum[((ai * 2 + bj) * 4 + m) * 64] = pack8(v);
; #pragma unroll
;         for (int nn = 0; nn < 2; ++nn)
; #pragma unroll
;           for (int j = 0; j < 4; ++j) acc[ai][bj][m][nn][j] = v[nn * 4 + j];
	v_fmamk_f32 v54, v54, 0xbfb8aa3b, v170
	v_exp_f32_e32 v54, v54
	v_fmamk_f32 v55, v55, 0xbfb8aa3b, v170
	v_exp_f32_e32 v55, v55
	v_fmamk_f32 v56, v56, 0xbfb8aa3b, v170
	v_exp_f32_e32 v56, v56
	v_fmamk_f32 v57, v57, 0xbfb8aa3b, v170
	v_exp_f32_e32 v57, v57
	v_fmamk_f32 v50, v50, 0xbfb8aa3b, v252
	v_exp_f32_e32 v50, v50
	v_fmamk_f32 v51, v51, 0xbfb8aa3b, v252
	v_exp_f32_e32 v51, v51
	v_fmamk_f32 v52, v52, 0xbfb8aa3b, v252
	v_exp_f32_e32 v52, v52
	v_fmamk_f32 v53, v53, 0xbfb8aa3b, v252
	v_exp_f32_e32 v53, v53
	v_fmamk_f32 v10, v10, 0xbfb8aa3b, v253
	v_exp_f32_e32 v10, v10
	v_fmamk_f32 v11, v11, 0xbfb8aa3b, v253
	v_exp_f32_e32 v11, v11
	v_fmamk_f32 v12, v12, 0xbfb8aa3b, v253
	v_exp_f32_e32 v12, v12
	v_fmamk_f32 v13, v13, 0xbfb8aa3b, v253
	v_exp_f32_e32 v13, v13
	v_fmamk_f32 v2, v2, 0xbfb8aa3b, v162
	v_exp_f32_e32 v2, v2
	v_fmamk_f32 v3, v3, 0xbfb8aa3b, v162
	v_exp_f32_e32 v3, v3
	v_fmamk_f32 v4, v4, 0xbfb8aa3b, v162
	v_exp_f32_e32 v4, v4
	v_fmamk_f32 v5, v5, 0xbfb8aa3b, v162
	v_exp_f32_e32 v5, v5
	v_add_f32_e32 v54, 1.0, v54
	v_add_f32_e32 v55, 1.0, v55
	v_lshlrev_b32_e32 v156, 16, v190
	v_and_b32_e32 v157, 0xffff0000, v190
	v_rcp_f32_e32 v54, v54
	v_rcp_f32_e32 v55, v55
	v_add_f32_e32 v56, 1.0, v56
	v_add_f32_e32 v57, 1.0, v57
	v_lshlrev_b32_e32 v164, 16, v191
	v_and_b32_e32 v165, 0xffff0000, v191
	v_rcp_f32_e32 v56, v56
	v_rcp_f32_e32 v57, v57
	v_mul_f32_e32 v54, v54, v156
	v_mul_f32_e32 v55, v55, v157
	v_mul_f32_e32 v56, v56, v164
	v_mul_f32_e32 v57, v57, v165
	v_add_f32_e32 v50, 1.0, v50
	v_add_f32_e32 v51, 1.0, v51
	v_lshlrev_b32_e32 v156, 16, v192
	v_and_b32_e32 v157, 0xffff0000, v192
	v_rcp_f32_e32 v50, v50
	v_rcp_f32_e32 v51, v51
	v_add_f32_e32 v52, 1.0, v52
	v_add_f32_e32 v53, 1.0, v53
	v_lshlrev_b32_e32 v164, 16, v193
	v_and_b32_e32 v165, 0xffff0000, v193
	v_rcp_f32_e32 v52, v52
	v_rcp_f32_e32 v53, v53
	v_fmac_f32_e32 v54, v50, v156
	v_fmac_f32_e32 v55, v51, v157
	v_fmac_f32_e32 v56, v52, v164
	v_fmac_f32_e32 v57, v53, v165
	v_add_f32_e32 v10, 1.0, v10
	v_add_f32_e32 v11, 1.0, v11
	v_lshlrev_b32_e32 v156, 16, v194
	v_and_b32_e32 v157, 0xffff0000, v194
	v_rcp_f32_e32 v10, v10
	v_rcp_f32_e32 v11, v11
	v_add_f32_e32 v12, 1.0, v12
	v_add_f32_e32 v13, 1.0, v13
	v_lshlrev_b32_e32 v164, 16, v195
	v_and_b32_e32 v165, 0xffff0000, v195
	v_rcp_f32_e32 v12, v12
	v_rcp_f32_e32 v13, v13
	v_fmac_f32_e32 v54, v10, v156
	v_fmac_f32_e32 v55, v11, v157
	v_fmac_f32_e32 v56, v12, v164
	v_fmac_f32_e32 v57, v13, v165
	v_add_f32_e32 v2, 1.0, v2
	v_add_f32_e32 v3, 1.0, v3
	v_lshlrev_b32_e32 v156, 16, v196
	v_and_b32_e32 v157, 0xffff0000, v196
	v_rcp_f32_e32 v2, v2
	v_rcp_f32_e32 v3, v3
	v_add_f32_e32 v4, 1.0, v4
	v_add_f32_e32 v5, 1.0, v5
	v_lshlrev_b32_e32 v164, 16, v197
	v_and_b32_e32 v165, 0xffff0000, v197
	v_rcp_f32_e32 v4, v4
	v_rcp_f32_e32 v5, v5
	v_fmac_f32_e32 v54, v2, v156
	v_fmac_f32_e32 v55, v3, v157
	v_fmac_f32_e32 v56, v4, v164
	v_fmac_f32_e32 v57, v5, v165
	v_lshrrev_b32_e32 v156, 8, v168
	v_lshlrev_b32_e32 v156, 6, v156
	v_bfe_u32 v157, v168, 4, 2
	v_lshl_add_u32 v156, v157, 2, v156
	v_mul_u32_u24_e32 v156, 0x84, v156
	v_lshlrev_b32_e32 v157, 4, v155
	v_and_b32_e32 v164, 15, v168
	v_add3_u32 v156, v156, v157, v164
	v_lshlrev_b32_e32 v156, 2, v156
	v_lshrrev_b32_e32 v157, 3, v168
	v_lshlrev_b32_e32 v165, 11, v157
	v_mul_u32_u24_e32 v157, 0x84, v157
	v_and_b32_e32 v164, 7, v168
	v_lshl_add_u32 v157, v164, 3, v157
	v_lshlrev_b32_e32 v157, 2, v157
	v_lshl_add_u32 v165, v164, 4, v165
	v_mov_b32_e32 v164, v165
	s_waitcnt lgkmcnt(0)
	s_barrier
	ds_write_b32 v156, v158 offset:0
	ds_write_b32 v156, v159 offset:528
	ds_write_b32 v156, v160 offset:1056
	ds_write_b32 v156, v161 offset:1584
	ds_write_b32 v156, v146 offset:8448
	ds_write_b32 v156, v147 offset:8976
	ds_write_b32 v156, v148 offset:9504
	ds_write_b32 v156, v149 offset:10032
	ds_write_b32 v156, v134 offset:16896
	ds_write_b32 v156, v135 offset:17424
	ds_write_b32 v156, v136 offset:17952
	ds_write_b32 v156, v137 offset:18480
	ds_write_b32 v156, v122 offset:25344
	ds_write_b32 v156, v123 offset:25872
	ds_write_b32 v156, v124 offset:26400
	ds_write_b32 v156, v125 offset:26928
	s_waitcnt lgkmcnt(0)
	s_barrier
	s_add_i32 s0, s12, 0
	s_lshl_b32 s0, s0, 11
	s_lshl_b32 s1, s23, 7
	s_add_u32 s0, s0, s1
	s_add_u32 s0, s36, s0
	s_addc_u32 s1, s37, 0
	ds_read_b128 v[230:233], v157 offset:0
	ds_read_b128 v[234:237], v157 offset:16
	ds_read_b128 v[238:241], v157 offset:33792
	ds_read_b128 v[242:245], v157 offset:33808
	s_waitcnt lgkmcnt(2)
	v_cvt_pk_bf16_f32 v230, v230, v231
	v_cvt_pk_bf16_f32 v231, v232, v233
	v_cvt_pk_bf16_f32 v232, v234, v235
	v_cvt_pk_bf16_f32 v233, v236, v237
	global_store_dwordx4 v164, v[230:233], s[0:1]
	s_waitcnt lgkmcnt(0)
	v_cvt_pk_bf16_f32 v238, v238, v239
	v_cvt_pk_bf16_f32 v239, v240, v241
	v_cvt_pk_bf16_f32 v240, v242, v243
	v_cvt_pk_bf16_f32 v241, v244, v245
	v_add_u32_e32 v164, 0x20000, v164
	global_store_dwordx4 v164, v[238:241], s[0:1]
	v_mov_b32_e32 v164, v165
	s_waitcnt lgkmcnt(0)
	s_barrier
	ds_write_b32 v156, v78 offset:0
	ds_write_b32 v156, v79 offset:528
	ds_write_b32 v156, v80 offset:1056
	ds_write_b32 v156, v81 offset:1584
	ds_write_b32 v156, v70 offset:8448
	ds_write_b32 v156, v71 offset:8976
	ds_write_b32 v156, v72 offset:9504
	ds_write_b32 v156, v73 offset:10032
	ds_write_b32 v156, v62 offset:16896
	ds_write_b32 v156, v63 offset:17424
	ds_write_b32 v156, v64 offset:17952
	ds_write_b32 v156, v65 offset:18480
	ds_write_b32 v156, v54 offset:25344
	ds_write_b32 v156, v55 offset:25872
	ds_write_b32 v156, v56 offset:26400
	ds_write_b32 v156, v57 offset:26928
	s_waitcnt lgkmcnt(0)
	s_barrier
	s_add_i32 s0, s12, 128
	s_lshl_b32 s0, s0, 11
	s_lshl_b32 s1, s23, 7
	s_add_u32 s0, s0, s1
	s_add_u32 s0, s36, s0
	s_addc_u32 s1, s37, 0
	ds_read_b128 v[230:233], v157 offset:0
	ds_read_b128 v[234:237], v157 offset:16
	ds_read_b128 v[238:241], v157 offset:33792
	ds_read_b128 v[242:245], v157 offset:33808
	s_waitcnt lgkmcnt(2)
	v_cvt_pk_bf16_f32 v230, v230, v231
	v_cvt_pk_bf16_f32 v231, v232, v233
	v_cvt_pk_bf16_f32 v232, v234, v235
	v_cvt_pk_bf16_f32 v233, v236, v237
	global_store_dwordx4 v164, v[230:233], s[0:1]
	s_waitcnt lgkmcnt(0)
	v_cvt_pk_bf16_f32 v238, v238, v239
	v_cvt_pk_bf16_f32 v239, v240, v241
	v_cvt_pk_bf16_f32 v240, v242, v243
	v_cvt_pk_bf16_f32 v241, v244, v245
	v_add_u32_e32 v164, 0x20000, v164
	global_store_dwordx4 v164, v[238:241], s[0:1]
	s_branch .LBB0_101
